# static s_setprio 1 for waves 4-7 around the diff-attention loops, plus G3 layer-0 second-round spreading, prep_unit prefetch, first K reads hoisted above the prefetch block
# speedup vs baseline: 1.0048x; 1.0027x over previous
.LBB0_924:
	s_ashr_i32 s2, s33, 8
	s_lshl_b32 s0, s33, 8
	s_lshl_b32 s35, s2, 14
	s_and_b32 s0, s0, 0x3f00
	v_mov_b32_e32 v50, v1
	s_or_b32 s0, s35, s0
	s_bfe_u32 s36, s33, 0x20006
	v_and_b32_e32 v3, 15, v50
	v_ashrrev_i32_e32 v2, 1, v50
	v_and_b32_e32 v2, 0xffffffe0, v2
	v_or_b32_e32 v4, s0, v3
	v_add_u32_e32 v140, v4, v2
	v_mad_i64_i32 v[4:5], s[0:1], v140, s21, v[134:135]
	s_lshl_b32 s12, s36, 7
	v_lshl_add_u64 v[4:5], v[4:5], 0, s[12:13]
	v_and_b32_e32 v136, 48, v50
	v_lshl_add_u64 v[4:5], v[4:5], 0, v[136:137]
	global_load_dwordx4 v[8:11], v[4:5], off offset:3136
	global_load_dwordx4 v[12:15], v[4:5], off offset:3200
	s_lshl_b32 s0, s2, 2
	s_lshl_b32 s1, s2, 3
	s_lshl_b32 s37, s36, 1
	s_or_b32 s2, s0, s36
	s_or_b32 s0, s37, s1
	s_ashr_i32 s1, s0, 31
	s_lshl_b32 s34, s36, 6
	s_lshl_b64 s[0:1], s[0:1], 2
	s_add_u32 s0, s88, s0
	s_addc_u32 s1, s89, s1
	global_load_dwordx2 v[4:5], v137, s[0:1]
	v_cmp_lt_i32_e32 vcc, v152, v153
	v_or_b32_e32 v142, 16, v140
	v_mad_i64_i32 v[16:17], s[0:1], v142, s21, v[134:135]
	v_cndmask_b32_e32 v2, v151, v152, vcc
	v_cmp_lt_i32_e32 vcc, v154, v153
	v_lshl_add_u64 v[16:17], v[16:17], 0, s[12:13]
	v_lshl_add_u64 v[20:21], v[16:17], 0, v[136:137]
	v_cndmask_b32_e32 v6, v151, v154, vcc
	v_lshlrev_b32_e32 v157, 2, v6
	v_lshlrev_b32_e32 v158, 2, v2
	global_load_dwordx4 v[16:19], v[20:21], off offset:3136
	s_mul_i32 s37, s2, 0x208000
	s_mul_hi_i32 s36, s2, 0x208000
	v_ashrrev_i32_e32 v161, 3, v50
	v_mov_b32_e32 v145, v137
	v_and_b32_e32 v159, 63, v50
	v_bfe_u32 v7, v50, 4, 2
	v_lshlrev_b32_e32 v66, 6, v161
	v_mul_lo_u32 v68, v161, s25
	v_lshlrev_b32_e32 v162, 6, v3
	v_mul_u32_u24_e32 v69, 0x48, v3
	v_ashrrev_i32_e32 v141, 31, v140
	v_ashrrev_i32_e32 v143, 31, v142
	v_lshlrev_b32_e32 v160, 2, v7
	v_lshlrev_b32_e32 v166, 1, v68
	v_lshlrev_b32_e32 v167, 1, v69
	v_mov_b32_e32 v68, v137
	v_mov_b32_e32 v69, v137
	v_mov_b32_e32 v70, 0
	v_mov_b32_e32 v71, v137
	v_mov_b32_e32 v72, v137
	v_mov_b32_e32 v73, v137
	v_mov_b32_e32 v74, 0
	v_mov_b32_e32 v75, v137
	v_mov_b32_e32 v76, v137
	v_mov_b32_e32 v77, v137
	v_mov_b32_e32 v78, 0
	v_mov_b32_e32 v79, v137
	v_mov_b32_e32 v80, v137
	v_mov_b32_e32 v81, v137
	v_mov_b32_e32 v90, 0
	v_mov_b32_e32 v91, v137
	v_mov_b32_e32 v92, v137
	v_mov_b32_e32 v93, v137
	v_mov_b32_e32 v94, 0
	v_mov_b32_e32 v95, v137
	v_mov_b32_e32 v96, v137
	v_mov_b32_e32 v97, v137
	v_mov_b32_e32 v98, 0
	v_mov_b32_e32 v99, v137
	v_mov_b32_e32 v100, v137
	v_mov_b32_e32 v101, v137
	v_mov_b32_e32 v102, 0
	v_mov_b32_e32 v103, v137
	v_mov_b32_e32 v104, v137
	v_mov_b32_e32 v105, v137
	v_mov_b32_e32 v106, 0
	v_mov_b32_e32 v107, v137
	v_mov_b32_e32 v108, v137
	v_mov_b32_e32 v109, v137
	v_mov_b32_e32 v110, 0
	v_mov_b32_e32 v111, v137
	v_mov_b32_e32 v112, v137
	v_mov_b32_e32 v113, v137
	v_mov_b32_e32 v118, 0
	v_mov_b32_e32 v119, v137
	s_waitcnt vmcnt(3)
	v_and_b32_e32 v23, 0xffff0000, v8
	v_lshlrev_b32_e32 v22, 16, v8
	v_and_b32_e32 v25, 0xffff0000, v9
	v_lshlrev_b32_e32 v24, 16, v9
	v_and_b32_e32 v9, 0xffff0000, v10
	v_lshlrev_b32_e32 v8, 16, v10
	v_and_b32_e32 v27, 0xffff0000, v11
	v_lshlrev_b32_e32 v26, 16, v11
	s_waitcnt vmcnt(2)
	v_and_b32_e32 v11, 0xffff0000, v12
	v_lshlrev_b32_e32 v10, 16, v12
	v_and_b32_e32 v29, 0xffff0000, v13
	v_lshlrev_b32_e32 v28, 16, v13
	v_pk_mul_f32 v[12:13], v[22:23], s[14:15] op_sel_hi:[1,0]
	v_pk_mul_f32 v[22:23], v[24:25], s[14:15] op_sel_hi:[1,0]
	v_and_b32_sdwa v6, v12, v155 dst_sel:DWORD dst_unused:UNUSED_PAD src0_sel:WORD_1 src1_sel:DWORD
	v_pk_mul_f32 v[8:9], v[8:9], s[14:15] op_sel_hi:[1,0]
	v_pk_mul_f32 v[24:25], v[26:27], s[14:15] op_sel_hi:[1,0]
	v_and_b32_sdwa v2, v13, v155 dst_sel:DWORD dst_unused:UNUSED_PAD src0_sel:WORD_1 src1_sel:DWORD
	v_and_b32_sdwa v26, v23, v155 dst_sel:DWORD dst_unused:UNUSED_PAD src0_sel:WORD_1 src1_sel:DWORD
	v_and_b32_sdwa v27, v22, v155 dst_sel:DWORD dst_unused:UNUSED_PAD src0_sel:WORD_1 src1_sel:DWORD
	v_add3_u32 v38, v12, v6, s22
	v_and_b32_sdwa v30, v9, v155 dst_sel:DWORD dst_unused:UNUSED_PAD src0_sel:WORD_1 src1_sel:DWORD
	v_and_b32_sdwa v31, v8, v155 dst_sel:DWORD dst_unused:UNUSED_PAD src0_sel:WORD_1 src1_sel:DWORD
	v_add3_u32 v34, v13, v2, s22
	v_add3_u32 v35, v23, v26, s22
	v_add3_u32 v39, v22, v27, s22
	v_and_b32_e32 v2, 0xffff0000, v38
	v_add3_u32 v36, v9, v30, s22
	v_add3_u32 v40, v8, v31, s22
	v_and_b32_e32 v6, 0xffff0000, v34
	v_and_b32_e32 v9, 0xffff0000, v35
	v_and_b32_e32 v8, 0xffff0000, v39
	v_mul_f32_e32 v2, v2, v2
	v_pk_mul_f32 v[8:9], v[8:9], v[8:9]
	v_fmac_f32_e32 v2, v6, v6
	v_and_b32_e32 v13, 0xffff0000, v36
	v_and_b32_e32 v12, 0xffff0000, v40
	v_add_f32_e32 v2, v8, v2
	v_pk_mul_f32 v[12:13], v[12:13], v[12:13]
	v_add_f32_e32 v2, v9, v2
	v_and_b32_sdwa v32, v25, v155 dst_sel:DWORD dst_unused:UNUSED_PAD src0_sel:WORD_1 src1_sel:DWORD
	v_and_b32_sdwa v33, v24, v155 dst_sel:DWORD dst_unused:UNUSED_PAD src0_sel:WORD_1 src1_sel:DWORD
	v_add_f32_e32 v2, v12, v2
	v_pk_mul_f32 v[8:9], v[10:11], s[14:15] op_sel_hi:[1,0]
	v_add3_u32 v37, v25, v32, s22
	v_add3_u32 v41, v24, v33, s22
	v_add_f32_e32 v2, v13, v2
	v_and_b32_sdwa v13, v8, v155 dst_sel:DWORD dst_unused:UNUSED_PAD src0_sel:WORD_1 src1_sel:DWORD
	v_and_b32_e32 v23, 0xffff0000, v37
	v_and_b32_e32 v22, 0xffff0000, v41
	v_add3_u32 v46, v8, v13, s22
	v_pk_mul_f32 v[22:23], v[22:23], v[22:23]
	v_pk_mul_f32 v[10:11], v[28:29], s[14:15] op_sel_hi:[1,0]
	v_and_b32_sdwa v12, v9, v155 dst_sel:DWORD dst_unused:UNUSED_PAD src0_sel:WORD_1 src1_sel:DWORD
	v_and_b32_e32 v8, 0xffff0000, v46
	v_add_f32_e32 v2, v22, v2
	v_and_b32_sdwa v22, v11, v155 dst_sel:DWORD dst_unused:UNUSED_PAD src0_sel:WORD_1 src1_sel:DWORD
	v_add3_u32 v42, v9, v12, s22
	v_mul_f32_e32 v12, v8, v8
	v_and_b32_sdwa v8, v10, v155 dst_sel:DWORD dst_unused:UNUSED_PAD src0_sel:WORD_1 src1_sel:DWORD
	v_and_b32_e32 v9, 0xffff0000, v42
	v_add3_u32 v43, v11, v22, s22
	v_add3_u32 v47, v10, v8, s22
	v_fmac_f32_e32 v12, v9, v9
	v_and_b32_e32 v9, 0xffff0000, v43
	v_and_b32_e32 v8, 0xffff0000, v47
	v_pk_mul_f32 v[8:9], v[8:9], v[8:9]
	v_add_f32_e32 v2, v23, v2
	v_add_f32_e32 v8, v8, v12
	v_add_f32_e32 v10, v9, v8
	v_and_b32_e32 v9, 0xffff0000, v14
	v_lshlrev_b32_e32 v8, 16, v14
	ds_bpermute_b32 v6, v158, v2
	v_pk_mul_f32 v[8:9], v[8:9], s[14:15] op_sel_hi:[1,0]
	v_perm_b32 v37, v37, v41, s26
	v_and_b32_sdwa v11, v9, v155 dst_sel:DWORD dst_unused:UNUSED_PAD src0_sel:WORD_1 src1_sel:DWORD
	v_and_b32_sdwa v12, v8, v155 dst_sel:DWORD dst_unused:UNUSED_PAD src0_sel:WORD_1 src1_sel:DWORD
	v_add3_u32 v44, v9, v11, s22
	v_add3_u32 v48, v8, v12, s22
	v_and_b32_e32 v9, 0xffff0000, v44
	v_and_b32_e32 v8, 0xffff0000, v48
	v_pk_mul_f32 v[8:9], v[8:9], v[8:9]
	s_waitcnt lgkmcnt(0)
	v_add_f32_e32 v2, v2, v6
	v_add_f32_e32 v8, v8, v10
	ds_bpermute_b32 v6, v157, v2
	v_add_f32_e32 v10, v9, v8
	v_and_b32_e32 v9, 0xffff0000, v15
	v_lshlrev_b32_e32 v8, 16, v15
	v_pk_mul_f32 v[8:9], v[8:9], s[14:15] op_sel_hi:[1,0]
	s_waitcnt lgkmcnt(0)
	v_add_f32_e32 v2, v2, v6
	v_and_b32_sdwa v11, v9, v155 dst_sel:DWORD dst_unused:UNUSED_PAD src0_sel:WORD_1 src1_sel:DWORD
	v_and_b32_sdwa v12, v8, v155 dst_sel:DWORD dst_unused:UNUSED_PAD src0_sel:WORD_1 src1_sel:DWORD
	v_add3_u32 v15, v9, v11, s22
	v_add3_u32 v45, v8, v12, s22
	v_and_b32_e32 v9, 0xffff0000, v15
	v_and_b32_e32 v8, 0xffff0000, v45
	v_pk_mul_f32 v[8:9], v[8:9], v[8:9]
	s_waitcnt vmcnt(1)
	v_mul_f32_e32 v2, v4, v2
	v_add_f32_e32 v8, v8, v10
	v_mul_f32_e32 v6, 0x4f800000, v2
	v_cmp_gt_f32_e32 vcc, s23, v2
	v_add_f32_e32 v8, v9, v8
	ds_bpermute_b32 v9, v158, v8
	v_cndmask_b32_e32 v2, v2, v6, vcc
	v_sqrt_f32_e32 v6, v2
	v_perm_b32 v36, v36, v40, s26
	v_perm_b32 v35, v35, v39, s26
	s_waitcnt lgkmcnt(0)
	v_add_f32_e32 v8, v8, v9
	v_add_u32_e32 v13, -1, v6
	v_fma_f32 v23, -v13, v6, v2
	ds_bpermute_b32 v9, v157, v8
	v_cmp_ge_f32_e64 s[0:1], 0, v23
	v_add_u32_e32 v11, 1, v6
	v_perm_b32 v34, v34, v38, s26
	v_cndmask_b32_e64 v10, v6, v13, s[0:1]
	v_fma_f32 v6, -v11, v6, v2
	v_cmp_lt_f32_e64 s[0:1], 0, v6
	s_waitcnt lgkmcnt(0)
	v_add_f32_e32 v8, v8, v9
	v_mul_f32_e32 v12, v5, v8
	v_cndmask_b32_e64 v6, v10, v11, s[0:1]
	v_mul_f32_e32 v10, 0x37800000, v6
	v_cndmask_b32_e32 v6, v6, v10, vcc
	global_load_dwordx4 v[8:11], v[20:21], off offset:3200
	v_mul_f32_e32 v13, 0x4f800000, v12
	v_cmp_gt_f32_e32 vcc, s23, v12
	v_cmp_class_f32_e64 s[0:1], v2, v139
	v_perm_b32 v45, v15, v45, s26
	v_cndmask_b32_e32 v14, v12, v13, vcc
	s_waitcnt vmcnt(1)
	v_and_b32_e32 v13, 0xffff0000, v16
	v_lshlrev_b32_e32 v12, 16, v16
	v_pk_mul_f32 v[12:13], v[12:13], s[14:15] op_sel_hi:[1,0]
	v_sqrt_f32_e32 v20, v14
	v_and_b32_sdwa v22, v12, v155 dst_sel:DWORD dst_unused:UNUSED_PAD src0_sel:WORD_1 src1_sel:DWORD
	v_and_b32_sdwa v16, v13, v155 dst_sel:DWORD dst_unused:UNUSED_PAD src0_sel:WORD_1 src1_sel:DWORD
	v_add3_u32 v49, v12, v22, s22
	v_add3_u32 v16, v13, v16, s22
	v_and_b32_e32 v12, 0xffff0000, v49
	v_mul_f32_e32 v22, v12, v12
	v_and_b32_e32 v12, 0xffff0000, v16
	v_fmac_f32_e32 v22, v12, v12
	v_and_b32_e32 v13, 0xffff0000, v17
	v_lshlrev_b32_e32 v12, 16, v17
	v_pk_mul_f32 v[12:13], v[12:13], s[14:15] op_sel_hi:[1,0]
	v_cndmask_b32_e64 v2, v6, v2, s[0:1]
	v_and_b32_sdwa v17, v13, v155 dst_sel:DWORD dst_unused:UNUSED_PAD src0_sel:WORD_1 src1_sel:DWORD
	v_and_b32_sdwa v23, v12, v155 dst_sel:DWORD dst_unused:UNUSED_PAD src0_sel:WORD_1 src1_sel:DWORD
	v_add3_u32 v17, v13, v17, s22
	v_add3_u32 v51, v12, v23, s22
	v_and_b32_e32 v13, 0xffff0000, v17
	v_and_b32_e32 v12, 0xffff0000, v51
	v_pk_mul_f32 v[12:13], v[12:13], v[12:13]
	v_add_u32_e32 v6, -1, v20
	v_add_f32_e32 v12, v12, v22
	v_add_f32_e32 v22, v13, v12
	v_and_b32_e32 v13, 0xffff0000, v18
	v_lshlrev_b32_e32 v12, 16, v18
	v_pk_mul_f32 v[12:13], v[12:13], s[14:15] op_sel_hi:[1,0]
	v_fma_f32 v21, -v6, v20, v14
	v_and_b32_sdwa v18, v13, v155 dst_sel:DWORD dst_unused:UNUSED_PAD src0_sel:WORD_1 src1_sel:DWORD
	v_and_b32_sdwa v23, v12, v155 dst_sel:DWORD dst_unused:UNUSED_PAD src0_sel:WORD_1 src1_sel:DWORD
	v_add3_u32 v54, v13, v18, s22
	v_add3_u32 v55, v12, v23, s22
	v_and_b32_e32 v13, 0xffff0000, v54
	v_and_b32_e32 v12, 0xffff0000, v55
	v_pk_mul_f32 v[12:13], v[12:13], v[12:13]
	v_cmp_ge_f32_e64 s[0:1], 0, v21
	v_add_f32_e32 v12, v12, v22
	v_add_f32_e32 v18, v13, v12
	v_and_b32_e32 v13, 0xffff0000, v19
	v_lshlrev_b32_e32 v12, 16, v19
	v_pk_mul_f32 v[12:13], v[12:13], s[14:15] op_sel_hi:[1,0]
	v_cndmask_b32_e64 v6, v20, v6, s[0:1]
	v_and_b32_sdwa v19, v13, v155 dst_sel:DWORD dst_unused:UNUSED_PAD src0_sel:WORD_1 src1_sel:DWORD
	v_and_b32_sdwa v22, v12, v155 dst_sel:DWORD dst_unused:UNUSED_PAD src0_sel:WORD_1 src1_sel:DWORD
	v_add3_u32 v56, v13, v19, s22
	v_add3_u32 v57, v12, v22, s22
	v_and_b32_e32 v13, 0xffff0000, v56
	v_and_b32_e32 v12, 0xffff0000, v57
	v_pk_mul_f32 v[12:13], v[12:13], v[12:13]
	v_xor_b32_e32 v2, 0x80000000, v2
	v_add_f32_e32 v12, v12, v18
	v_add_f32_e32 v12, v13, v12
	ds_bpermute_b32 v13, v158, v12
	v_add_u32_e32 v18, 1, v20
	v_fma_f32 v19, -v18, v20, v14
	v_cmp_lt_f32_e64 s[0:1], 0, v19
	v_perm_b32 v41, v56, v57, s26
	s_waitcnt lgkmcnt(0)
	v_add_f32_e32 v12, v12, v13
	ds_bpermute_b32 v13, v157, v12
	v_cndmask_b32_e64 v6, v6, v18, s[0:1]
	v_mul_f32_e32 v18, 0x37800000, v6
	v_cndmask_b32_e32 v6, v6, v18, vcc
	v_cmp_class_f32_e64 s[0:1], v14, v139
	s_waitcnt lgkmcnt(0)
	v_add_f32_e32 v12, v12, v13
	v_mul_f32_e32 v4, v4, v12
	v_mul_f32_e32 v12, 0x4f800000, v4
	v_cmp_gt_f32_e32 vcc, s23, v4
	v_cndmask_b32_e64 v6, v6, v14, s[0:1]
	v_xor_b32_e32 v6, 0x80000000, v6
	v_cndmask_b32_e32 v4, v4, v12, vcc
	v_sqrt_f32_e32 v18, v4
	v_perm_b32 v40, v54, v55, s26
	s_waitcnt vmcnt(0)
	v_and_b32_e32 v13, 0xffff0000, v8
	v_lshlrev_b32_e32 v12, 16, v8
	v_pk_mul_f32 v[12:13], v[12:13], s[14:15] op_sel_hi:[1,0]
	v_add_u32_e32 v14, -1, v18
	v_and_b32_sdwa v20, v12, v155 dst_sel:DWORD dst_unused:UNUSED_PAD src0_sel:WORD_1 src1_sel:DWORD
	v_and_b32_sdwa v8, v13, v155 dst_sel:DWORD dst_unused:UNUSED_PAD src0_sel:WORD_1 src1_sel:DWORD
	v_add3_u32 v59, v12, v20, s22
	v_add3_u32 v58, v13, v8, s22
	v_and_b32_e32 v8, 0xffff0000, v59
	v_mul_f32_e32 v20, v8, v8
	v_and_b32_e32 v8, 0xffff0000, v58
	v_and_b32_e32 v13, 0xffff0000, v9
	v_lshlrev_b32_e32 v12, 16, v9
	v_fmac_f32_e32 v20, v8, v8
	v_pk_mul_f32 v[8:9], v[12:13], s[14:15] op_sel_hi:[1,0]
	v_fma_f32 v19, -v14, v18, v4
	v_and_b32_sdwa v12, v9, v155 dst_sel:DWORD dst_unused:UNUSED_PAD src0_sel:WORD_1 src1_sel:DWORD
	v_and_b32_sdwa v13, v8, v155 dst_sel:DWORD dst_unused:UNUSED_PAD src0_sel:WORD_1 src1_sel:DWORD
	v_add3_u32 v60, v9, v12, s22
	v_add3_u32 v61, v8, v13, s22
	v_and_b32_e32 v9, 0xffff0000, v60
	v_and_b32_e32 v8, 0xffff0000, v61
	v_pk_mul_f32 v[8:9], v[8:9], v[8:9]
	v_cmp_ge_f32_e64 s[0:1], 0, v19
	v_add_f32_e32 v8, v8, v20
	v_add_f32_e32 v12, v9, v8
	v_and_b32_e32 v9, 0xffff0000, v10
	v_lshlrev_b32_e32 v8, 16, v10
	v_pk_mul_f32 v[8:9], v[8:9], s[14:15] op_sel_hi:[1,0]
	v_perm_b32 v39, v17, v51, s26
	v_and_b32_sdwa v10, v9, v155 dst_sel:DWORD dst_unused:UNUSED_PAD src0_sel:WORD_1 src1_sel:DWORD
	v_and_b32_sdwa v13, v8, v155 dst_sel:DWORD dst_unused:UNUSED_PAD src0_sel:WORD_1 src1_sel:DWORD
	v_add3_u32 v62, v9, v10, s22
	v_add3_u32 v63, v8, v13, s22
	v_and_b32_e32 v9, 0xffff0000, v62
	v_and_b32_e32 v8, 0xffff0000, v63
	v_pk_mul_f32 v[8:9], v[8:9], v[8:9]
	v_perm_b32 v38, v16, v49, s26
	v_add_f32_e32 v8, v8, v12
	v_add_f32_e32 v10, v9, v8
	v_and_b32_e32 v9, 0xffff0000, v11
	v_lshlrev_b32_e32 v8, 16, v11
	v_pk_mul_f32 v[8:9], v[8:9], s[14:15] op_sel_hi:[1,0]
	v_perm_b32 v44, v44, v48, s26
	v_and_b32_sdwa v11, v9, v155 dst_sel:DWORD dst_unused:UNUSED_PAD src0_sel:WORD_1 src1_sel:DWORD
	v_and_b32_sdwa v12, v8, v155 dst_sel:DWORD dst_unused:UNUSED_PAD src0_sel:WORD_1 src1_sel:DWORD
	v_add3_u32 v64, v9, v11, s22
	v_add3_u32 v65, v8, v12, s22
	v_and_b32_e32 v9, 0xffff0000, v64
	v_and_b32_e32 v8, 0xffff0000, v65
	v_pk_mul_f32 v[8:9], v[8:9], v[8:9]
	v_add_u32_e32 v11, 1, v18
	v_add_f32_e32 v8, v8, v10
	v_add_f32_e32 v8, v9, v8
	ds_bpermute_b32 v9, v158, v8
	v_fma_f32 v12, -v11, v18, v4
	v_cndmask_b32_e64 v10, v18, v14, s[0:1]
	v_cmp_lt_f32_e64 s[0:1], 0, v12
	v_perm_b32 v43, v43, v47, s26
	s_waitcnt lgkmcnt(0)
	v_add_f32_e32 v8, v8, v9
	ds_bpermute_b32 v9, v157, v8
	v_cndmask_b32_e64 v10, v10, v11, s[0:1]
	v_mul_f32_e32 v11, 0x37800000, v10
	v_cndmask_b32_e32 v10, v10, v11, vcc
	v_cmp_class_f32_e64 s[0:1], v4, v139
	s_waitcnt lgkmcnt(0)
	v_add_f32_e32 v8, v8, v9
	v_mul_f32_e32 v5, v5, v8
	v_mul_f32_e32 v8, 0x4f800000, v5
	v_cmp_gt_f32_e32 vcc, s23, v5
	v_cndmask_b32_e64 v4, v10, v4, s[0:1]
	v_xor_b32_e32 v10, 0x80000000, v4
	v_cndmask_b32_e32 v5, v5, v8, vcc
	v_sqrt_f32_e32 v8, v5
	v_mov_b32_e32 v12, v10
	v_mov_b32_e32 v13, v10
	v_perm_b32 v42, v42, v46, s26
	v_add_u32_e32 v4, -1, v8
	v_fma_f32 v9, -v4, v8, v5
	v_cmp_ge_f32_e64 s[0:1], 0, v9
	v_add_u32_e32 v9, 1, v8
	v_perm_b32 v49, v64, v65, s26
	v_cndmask_b32_e64 v4, v8, v4, s[0:1]
	v_fma_f32 v8, -v9, v8, v5
	v_cmp_lt_f32_e64 s[0:1], 0, v8
	v_perm_b32 v48, v62, v63, s26
	v_perm_b32 v47, v60, v61, s26
	v_cndmask_b32_e64 v4, v4, v9, s[0:1]
	v_mul_f32_e32 v8, 0x37800000, v4
	s_add_u32 s0, s3, s37
	v_cndmask_b32_e32 v4, v4, v8, vcc
	v_cmp_class_f32_e32 vcc, v5, v139
	s_addc_u32 s1, s15, s36
	s_and_b32 s38, s33, 0xffffff00
	v_cndmask_b32_e32 v4, v4, v5, vcc
	v_add_u32_e32 v11, s38, v161
	v_xor_b32_e32 v14, 0x80000000, v4
	v_add_u32_e32 v4, 0x8000, v11
	v_lshlrev_b32_e32 v8, 3, v50
	v_mad_i64_i32 v[4:5], s[36:37], v4, s21, v[134:135]
	v_and_b32_e32 v8, 56, v8
	v_lshl_add_u64 v[4:5], v[4:5], 0, s[12:13]
	v_lshlrev_b32_e32 v144, 1, v8
	v_mov_b64_e32 v[8:9], s[0:1]
	v_lshl_add_u64 v[4:5], v[4:5], 0, v[144:145]
	v_mad_i64_i32 v[8:9], s[0:1], v161, s24, v[8:9]
	v_lshl_add_u64 v[8:9], v[8:9], 0, v[144:145]
	global_load_dwordx4 v[18:21], v[4:5], off offset:3648
	global_load_dwordx4 v[22:25], v[8:9], off
	v_add_u32_e32 v4, 0x8040, v11
	v_mad_i64_i32 v[4:5], s[0:1], v4, s21, v[134:135]
	v_lshl_add_u64 v[4:5], v[4:5], 0, s[12:13]
	v_lshl_add_u64 v[4:5], v[4:5], 0, v[144:145]
	global_load_dwordx4 v[26:29], v[4:5], off offset:3648
	global_load_dwordx4 v[30:33], v[8:9], off offset:128
	v_mad_i64_i32 v[52:53], s[36:37], v161, s24, 0
	v_lshrrev_b32_e32 v4, 1, v161
	s_add_i32 s36, s38, 0x8080
	s_add_i32 s37, s38, 0x80c0
	v_xor_b32_e32 v4, v4, v50
	s_add_u32 s0, s8, s12
	v_lshlrev_b32_e32 v4, 3, v4
	s_addc_u32 s1, s9, 0
	v_and_b32_e32 v67, 56, v4
	v_bfe_u32 v4, v50, 1, 3
	v_lshl_add_u64 v[146:147], s[0:1], 0, v[144:145]
	v_mad_i64_i32 v[52:53], s[0:1], s2, v150, v[52:53]
	v_and_b32_e32 v50, 7, v50
	v_xor_b32_e32 v5, v7, v4
	v_bitop3_b32 v3, v7, v4, 4 bitop3:0x36
	v_lshl_or_b32 v52, v50, 4, v52
	v_lshlrev_b32_e32 v163, 3, v5
	v_lshlrev_b32_e32 v164, 3, v3
	v_mov_b32_e32 v3, v2
	v_mov_b32_e32 v4, v2
	v_mov_b32_e32 v5, v2
	v_mov_b32_e32 v11, v10
	v_mov_b32_e32 v7, v6
	v_mov_b32_e32 v8, v6
	v_mov_b32_e32 v9, v6
	v_mov_b32_e32 v15, v14
	v_mov_b32_e32 v16, v14
	v_mov_b32_e32 v17, v14
	v_perm_b32 v46, v58, v59, s26
	v_lshl_add_u64 v[148:149], s[10:11], 0, v[52:53]
	v_lshlrev_b32_e32 v145, 1, v66
	v_lshlrev_b32_e32 v165, 1, v67
	s_mov_b32 s12, 0
	s_mov_b32 s38, 0
	v_mov_b32_e32 v66, 0
	v_mov_b32_e32 v67, v137
	v_mov_b32_e32 v50, 0
	v_mov_b32_e32 v51, v137
	v_mov_b32_e32 v52, v137
	v_mov_b32_e32 v53, v137
	v_mov_b32_e32 v54, 0
	v_mov_b32_e32 v55, v137
	v_mov_b32_e32 v56, v137
	v_mov_b32_e32 v57, v137
	v_mov_b32_e32 v58, 0
	v_mov_b32_e32 v59, v137
	v_mov_b32_e32 v60, v137
	v_mov_b32_e32 v61, v137
	v_mov_b32_e32 v62, 0
	v_mov_b32_e32 v63, v137
	v_mov_b32_e32 v64, v137
	v_mov_b32_e32 v65, v137
	v_mov_b32_e32 v120, v137
	v_mov_b32_e32 v121, v137
	v_mov_b32_e32 v122, 0
	v_mov_b32_e32 v123, v137
	v_mov_b32_e32 v124, v137
	v_mov_b32_e32 v125, v137
	v_mov_b32_e32 v82, 0
	v_mov_b32_e32 v83, v137
	v_mov_b32_e32 v84, v137
	v_mov_b32_e32 v85, v137
	v_mov_b32_e32 v86, 0
	v_mov_b32_e32 v87, v137
	v_mov_b32_e32 v88, v137
	v_mov_b32_e32 v89, v137
	v_mov_b32_e32 v114, 0
	v_mov_b32_e32 v115, v137
	v_mov_b32_e32 v116, v137
	v_mov_b32_e32 v117, v137
	v_mov_b32_e32 v126, 0
	v_mov_b32_e32 v127, v137
	v_mov_b32_e32 v128, v137
	v_mov_b32_e32 v129, v137
	v_lshlrev_b32_e32 v246, 1, v162
	v_lshl_add_u32 v247, v164, 1, v246
	v_lshl_add_u32 v246, v163, 1, v246
	v_lshl_add_u32 v248, v160, 1, v167
	v_add_u32_e32 v244, v145, v165
	v_add_u32_e32 v245, v166, v144
	v_mov_b64_e32 v[240:241], s[4:5]
	v_mov_b64_e32 v[242:243], s[6:7]
	v_readfirstlane_b32 s98, v1
	s_cmpk_lt_u32 s98, 0x100
	s_cbranch_scc1 .Lnoprio_925
	s_setprio 1
.Lnoprio_925:
	s_movk_i32 s99, 0x4800
	v_lshlrev_b32_e32 v136, 1, v160
	s_barrier
	s_branch .LBB0_926

.LBB0_928:
	s_setprio 0
	v_cmp_gt_u32_e32 vcc, 32, v159
	v_mov_b32_e32 v2, 0
	v_mov_b32_e32 v3, 0
	s_and_saveexec_b64 s[0:1], vcc
	s_cbranch_execz .LBB0_923
	v_readlane_b32 s36, v239, 1
	v_lshlrev_b32_e32 v5, 2, v159
	v_readlane_b32 s38, v239, 3
	v_readlane_b32 s39, v239, 4
	v_readlane_b32 s40, v239, 5
	v_readlane_b32 s41, v239, 6
	v_readlane_b32 s42, v239, 7
	v_readlane_b32 s43, v239, 8
	v_readlane_b32 s44, v239, 9
	v_readlane_b32 s45, v239, 10
	global_load_dword v2, v5, s[38:39]
	global_load_dword v4, v5, s[40:41]
	s_nop 0
	global_load_dword v3, v5, s[42:43]
	s_nop 0
	global_load_dword v5, v5, s[44:45]
	v_readlane_b32 s37, v239, 2
	v_readlane_b32 s46, v239, 11
	v_readlane_b32 s47, v239, 12
	v_readlane_b32 s48, v239, 13
	v_readlane_b32 s49, v239, 14
	v_readlane_b32 s50, v239, 15
	v_readlane_b32 s51, v239, 16
	s_waitcnt vmcnt(0)
	v_pk_mul_f32 v[2:3], v[2:3], v[4:5]
	s_branch .LBB0_923

.LBB0_2158:
	s_ashr_i32 s2, s30, 8
	s_lshl_b32 s0, s30, 8
	s_lshl_b32 s33, s2, 14
	s_and_b32 s0, s0, 0x3f00
	v_mov_b32_e32 v50, v1
	s_or_b32 s0, s33, s0
	s_bfe_u32 s34, s30, 0x20006
	v_and_b32_e32 v3, 15, v50
	v_ashrrev_i32_e32 v2, 1, v50
	v_and_b32_e32 v2, 0xffffffe0, v2
	v_or_b32_e32 v4, s0, v3
	v_add_u32_e32 v138, v4, v2
	v_mov_b64_e32 v[4:5], s[60:61]
	v_mad_i64_i32 v[6:7], s[0:1], v138, s19, v[4:5]
	s_lshl_b32 s10, s34, 7
	v_lshl_add_u64 v[6:7], v[6:7], 0, s[10:11]
	v_and_b32_e32 v134, 48, v50
	v_lshl_add_u64 v[6:7], v[6:7], 0, v[134:135]
	global_load_dwordx4 v[10:13], v[6:7], off offset:3136
	global_load_dwordx4 v[14:17], v[6:7], off offset:3200
	s_lshl_b32 s0, s2, 2
	s_lshl_b32 s1, s2, 3
	s_lshl_b32 s35, s34, 1
	s_or_b32 s2, s0, s34
	s_or_b32 s0, s35, s1
	s_ashr_i32 s1, s0, 31
	s_lshl_b32 s31, s34, 6
	s_lshl_b64 s[0:1], s[0:1], 2
	s_add_u32 s0, s88, s0
	s_addc_u32 s1, s89, s1
	global_load_dwordx2 v[6:7], v135, s[0:1] offset:256
	v_cmp_lt_i32_e32 vcc, v148, v149
	v_or_b32_e32 v140, 16, v138
	v_mad_i64_i32 v[18:19], s[0:1], v140, s19, v[4:5]
	v_cndmask_b32_e32 v2, v137, v148, vcc
	v_lshlrev_b32_e32 v156, 2, v2
	v_cmp_lt_i32_e32 vcc, v150, v149
	v_lshl_add_u64 v[18:19], v[18:19], 0, s[10:11]
	v_lshl_add_u64 v[22:23], v[18:19], 0, v[134:135]
	v_cndmask_b32_e32 v8, v137, v150, vcc
	v_lshlrev_b32_e32 v155, 2, v8
	global_load_dwordx4 v[18:21], v[22:23], off offset:3136
	s_mul_i32 s35, s2, 0x208000
	s_mul_hi_i32 s34, s2, 0x208000
	v_ashrrev_i32_e32 v159, 3, v50
	v_mov_b32_e32 v143, v135
	v_and_b32_e32 v157, 63, v50
	v_bfe_u32 v8, v50, 4, 2
	v_lshlrev_b32_e32 v69, 6, v159
	v_mul_lo_u32 v71, v159, s23
	v_lshlrev_b32_e32 v160, 6, v3
	v_mul_u32_u24_e32 v72, 0x48, v3
	v_ashrrev_i32_e32 v139, 31, v138
	v_ashrrev_i32_e32 v141, 31, v140
	v_lshlrev_b32_e32 v158, 2, v8
	v_lshlrev_b32_e32 v164, 1, v71
	v_lshlrev_b32_e32 v165, 1, v72
	v_mov_b32_e32 v71, v135
	v_mov_b32_e32 v72, v135
	v_mov_b32_e32 v73, v135
	v_mov_b32_e32 v74, 0
	v_mov_b32_e32 v75, v135
	v_mov_b32_e32 v76, v135
	v_mov_b32_e32 v77, v135
	v_mov_b32_e32 v78, 0
	v_mov_b32_e32 v79, v135
	v_mov_b32_e32 v80, v135
	v_mov_b32_e32 v81, v135
	v_mov_b32_e32 v90, 0
	v_mov_b32_e32 v91, v135
	v_mov_b32_e32 v92, v135
	v_mov_b32_e32 v93, v135
	v_mov_b32_e32 v94, 0
	v_mov_b32_e32 v95, v135
	v_mov_b32_e32 v96, v135
	v_mov_b32_e32 v97, v135
	v_mov_b32_e32 v98, 0
	v_mov_b32_e32 v99, v135
	v_mov_b32_e32 v100, v135
	v_mov_b32_e32 v101, v135
	v_mov_b32_e32 v102, 0
	v_mov_b32_e32 v103, v135
	v_mov_b32_e32 v104, v135
	v_mov_b32_e32 v105, v135
	v_mov_b32_e32 v106, 0
	v_mov_b32_e32 v107, v135
	v_mov_b32_e32 v108, v135
	v_mov_b32_e32 v109, v135
	v_mov_b32_e32 v110, 0
	v_mov_b32_e32 v111, v135
	v_mov_b32_e32 v112, v135
	v_mov_b32_e32 v113, v135
	v_mov_b32_e32 v118, 0
	v_mov_b32_e32 v119, v135
	v_mov_b32_e32 v120, v135
	v_mov_b32_e32 v121, v135
	v_mov_b32_e32 v122, 0
	s_waitcnt vmcnt(3)
	v_and_b32_e32 v25, 0xffff0000, v10
	v_lshlrev_b32_e32 v24, 16, v10
	v_and_b32_e32 v27, 0xffff0000, v11
	v_lshlrev_b32_e32 v26, 16, v11
	v_pk_mul_f32 v[24:25], v[24:25], s[12:13] op_sel_hi:[1,0]
	v_and_b32_e32 v11, 0xffff0000, v12
	v_lshlrev_b32_e32 v10, 16, v12
	v_pk_mul_f32 v[26:27], v[26:27], s[12:13] op_sel_hi:[1,0]
	v_and_b32_sdwa v9, v24, v152 dst_sel:DWORD dst_unused:UNUSED_PAD src0_sel:WORD_1 src1_sel:DWORD
	v_and_b32_e32 v29, 0xffff0000, v13
	v_lshlrev_b32_e32 v28, 16, v13
	s_waitcnt vmcnt(2)
	v_and_b32_e32 v13, 0xffff0000, v14
	v_lshlrev_b32_e32 v12, 16, v14
	v_pk_mul_f32 v[10:11], v[10:11], s[12:13] op_sel_hi:[1,0]
	v_and_b32_sdwa v2, v25, v152 dst_sel:DWORD dst_unused:UNUSED_PAD src0_sel:WORD_1 src1_sel:DWORD
	v_and_b32_sdwa v14, v27, v152 dst_sel:DWORD dst_unused:UNUSED_PAD src0_sel:WORD_1 src1_sel:DWORD
	v_and_b32_sdwa v30, v26, v152 dst_sel:DWORD dst_unused:UNUSED_PAD src0_sel:WORD_1 src1_sel:DWORD
	v_add3_u32 v9, v24, v9, s20
	v_and_b32_sdwa v32, v11, v152 dst_sel:DWORD dst_unused:UNUSED_PAD src0_sel:WORD_1 src1_sel:DWORD
	v_and_b32_sdwa v33, v10, v152 dst_sel:DWORD dst_unused:UNUSED_PAD src0_sel:WORD_1 src1_sel:DWORD
	v_add3_u32 v38, v25, v2, s20
	v_add3_u32 v39, v27, v14, s20
	v_add3_u32 v40, v26, v30, s20
	v_and_b32_e32 v2, 0xffff0000, v9
	v_add3_u32 v36, v11, v32, s20
	v_add3_u32 v41, v10, v33, s20
	v_and_b32_e32 v14, 0xffff0000, v38
	v_and_b32_e32 v11, 0xffff0000, v39
	v_and_b32_e32 v10, 0xffff0000, v40
	v_mul_f32_e32 v2, v2, v2
	v_pk_mul_f32 v[28:29], v[28:29], s[12:13] op_sel_hi:[1,0]
	v_pk_mul_f32 v[10:11], v[10:11], v[10:11]
	v_fmac_f32_e32 v2, v14, v14
	v_and_b32_sdwa v34, v29, v152 dst_sel:DWORD dst_unused:UNUSED_PAD src0_sel:WORD_1 src1_sel:DWORD
	v_and_b32_sdwa v35, v28, v152 dst_sel:DWORD dst_unused:UNUSED_PAD src0_sel:WORD_1 src1_sel:DWORD
	v_and_b32_e32 v25, 0xffff0000, v36
	v_and_b32_e32 v24, 0xffff0000, v41
	v_add_f32_e32 v2, v10, v2
	v_add3_u32 v34, v29, v34, s20
	v_add3_u32 v35, v28, v35, s20
	v_pk_mul_f32 v[24:25], v[24:25], v[24:25]
	v_add_f32_e32 v2, v11, v2
	v_and_b32_e32 v27, 0xffff0000, v34
	v_and_b32_e32 v26, 0xffff0000, v35
	v_add_f32_e32 v2, v24, v2
	v_pk_mul_f32 v[26:27], v[26:27], v[26:27]
	v_add_f32_e32 v2, v25, v2
	v_add_f32_e32 v2, v26, v2
	v_add_f32_e32 v2, v27, v2
	ds_bpermute_b32 v14, v156, v2
	v_pk_mul_f32 v[10:11], v[12:13], s[12:13] op_sel_hi:[1,0]
	v_and_b32_e32 v31, 0xffff0000, v15
	v_and_b32_sdwa v24, v10, v152 dst_sel:DWORD dst_unused:UNUSED_PAD src0_sel:WORD_1 src1_sel:DWORD
	v_lshlrev_b32_e32 v30, 16, v15
	s_waitcnt lgkmcnt(0)
	v_add_f32_e32 v2, v2, v14
	ds_bpermute_b32 v14, v155, v2
	v_and_b32_sdwa v15, v11, v152 dst_sel:DWORD dst_unused:UNUSED_PAD src0_sel:WORD_1 src1_sel:DWORD
	v_add3_u32 v46, v10, v24, s20
	v_add3_u32 v42, v11, v15, s20
	v_and_b32_e32 v10, 0xffff0000, v46
	s_waitcnt lgkmcnt(0)
	v_add_f32_e32 v2, v2, v14
	s_waitcnt vmcnt(1)
	v_mul_f32_e32 v2, v6, v2
	v_mul_f32_e32 v11, 0x4f800000, v2
	v_cmp_gt_f32_e32 vcc, s21, v2
	v_pk_mul_f32 v[12:13], v[30:31], s[12:13] op_sel_hi:[1,0]
	v_mul_f32_e32 v15, v10, v10
	v_cndmask_b32_e32 v2, v2, v11, vcc
	v_and_b32_e32 v11, 0xffff0000, v42
	v_fmac_f32_e32 v15, v11, v11
	v_and_b32_sdwa v10, v13, v152 dst_sel:DWORD dst_unused:UNUSED_PAD src0_sel:WORD_1 src1_sel:DWORD
	v_and_b32_sdwa v11, v12, v152 dst_sel:DWORD dst_unused:UNUSED_PAD src0_sel:WORD_1 src1_sel:DWORD
	v_add3_u32 v43, v13, v10, s20
	v_add3_u32 v47, v12, v11, s20
	v_and_b32_e32 v11, 0xffff0000, v43
	v_and_b32_e32 v10, 0xffff0000, v47
	v_pk_mul_f32 v[10:11], v[10:11], v[10:11]
	v_sqrt_f32_e32 v14, v2
	v_add_f32_e32 v10, v10, v15
	v_add_f32_e32 v12, v11, v10
	v_and_b32_e32 v11, 0xffff0000, v16
	v_lshlrev_b32_e32 v10, 16, v16
	v_pk_mul_f32 v[10:11], v[10:11], s[12:13] op_sel_hi:[1,0]
	v_add_u32_e32 v24, -1, v14
	v_and_b32_sdwa v13, v11, v152 dst_sel:DWORD dst_unused:UNUSED_PAD src0_sel:WORD_1 src1_sel:DWORD
	v_and_b32_sdwa v15, v10, v152 dst_sel:DWORD dst_unused:UNUSED_PAD src0_sel:WORD_1 src1_sel:DWORD
	v_add3_u32 v44, v11, v13, s20
	v_add3_u32 v48, v10, v15, s20
	v_and_b32_e32 v11, 0xffff0000, v44
	v_and_b32_e32 v10, 0xffff0000, v48
	v_pk_mul_f32 v[10:11], v[10:11], v[10:11]
	v_fma_f32 v25, -v24, v14, v2
	v_add_f32_e32 v10, v10, v12
	v_add_f32_e32 v12, v11, v10
	v_and_b32_e32 v11, 0xffff0000, v17
	v_lshlrev_b32_e32 v10, 16, v17
	v_pk_mul_f32 v[10:11], v[10:11], s[12:13] op_sel_hi:[1,0]
	v_cmp_ge_f32_e64 s[0:1], 0, v25
	v_and_b32_sdwa v13, v11, v152 dst_sel:DWORD dst_unused:UNUSED_PAD src0_sel:WORD_1 src1_sel:DWORD
	v_and_b32_sdwa v15, v10, v152 dst_sel:DWORD dst_unused:UNUSED_PAD src0_sel:WORD_1 src1_sel:DWORD
	v_add3_u32 v45, v11, v13, s20
	v_add3_u32 v49, v10, v15, s20
	v_and_b32_e32 v11, 0xffff0000, v45
	v_and_b32_e32 v10, 0xffff0000, v49
	v_pk_mul_f32 v[10:11], v[10:11], v[10:11]
	v_add_u32_e32 v13, 1, v14
	v_add_f32_e32 v10, v10, v12
	v_add_f32_e32 v10, v11, v10
	ds_bpermute_b32 v11, v156, v10
	v_cndmask_b32_e64 v12, v14, v24, s[0:1]
	v_fma_f32 v14, -v13, v14, v2
	v_cmp_lt_f32_e64 s[0:1], 0, v14
	v_perm_b32 v37, v34, v35, s24
	s_waitcnt lgkmcnt(0)
	v_add_f32_e32 v10, v10, v11
	ds_bpermute_b32 v11, v155, v10
	v_cndmask_b32_e64 v12, v12, v13, s[0:1]
	v_mul_f32_e32 v13, 0x37800000, v12
	v_cndmask_b32_e32 v14, v12, v13, vcc
	v_cmp_class_f32_e64 s[0:1], v2, v151
	s_waitcnt lgkmcnt(0)
	v_add_f32_e32 v10, v10, v11
	v_mul_f32_e32 v15, v7, v10
	global_load_dwordx4 v[10:13], v[22:23], off offset:3200
	v_mul_f32_e32 v16, 0x4f800000, v15
	v_cmp_gt_f32_e32 vcc, s21, v15
	v_cndmask_b32_e64 v2, v14, v2, s[0:1]
	s_waitcnt vmcnt(1)
	v_lshlrev_b32_e32 v14, 16, v18
	v_cndmask_b32_e32 v16, v15, v16, vcc
	v_and_b32_e32 v15, 0xffff0000, v18
	v_pk_mul_f32 v[14:15], v[14:15], s[12:13] op_sel_hi:[1,0]
	v_sqrt_f32_e32 v17, v16
	v_and_b32_sdwa v24, v14, v152 dst_sel:DWORD dst_unused:UNUSED_PAD src0_sel:WORD_1 src1_sel:DWORD
	v_and_b32_sdwa v18, v15, v152 dst_sel:DWORD dst_unused:UNUSED_PAD src0_sel:WORD_1 src1_sel:DWORD
	v_add3_u32 v54, v14, v24, s20
	v_add3_u32 v51, v15, v18, s20
	v_and_b32_e32 v14, 0xffff0000, v54
	v_mul_f32_e32 v18, v14, v14
	v_and_b32_e32 v14, 0xffff0000, v51
	v_fmac_f32_e32 v18, v14, v14
	v_and_b32_e32 v15, 0xffff0000, v19
	v_lshlrev_b32_e32 v14, 16, v19
	v_pk_mul_f32 v[14:15], v[14:15], s[12:13] op_sel_hi:[1,0]
	v_add_u32_e32 v22, -1, v17
	v_and_b32_sdwa v19, v15, v152 dst_sel:DWORD dst_unused:UNUSED_PAD src0_sel:WORD_1 src1_sel:DWORD
	v_and_b32_sdwa v24, v14, v152 dst_sel:DWORD dst_unused:UNUSED_PAD src0_sel:WORD_1 src1_sel:DWORD
	v_add3_u32 v55, v15, v19, s20
	v_add3_u32 v56, v14, v24, s20
	v_and_b32_e32 v15, 0xffff0000, v55
	v_and_b32_e32 v14, 0xffff0000, v56
	v_pk_mul_f32 v[14:15], v[14:15], v[14:15]
	v_fma_f32 v23, -v22, v17, v16
	v_add_f32_e32 v14, v14, v18
	v_add_f32_e32 v18, v15, v14
	v_and_b32_e32 v15, 0xffff0000, v20
	v_lshlrev_b32_e32 v14, 16, v20
	v_pk_mul_f32 v[14:15], v[14:15], s[12:13] op_sel_hi:[1,0]
	v_cmp_ge_f32_e64 s[0:1], 0, v23
	v_and_b32_sdwa v19, v15, v152 dst_sel:DWORD dst_unused:UNUSED_PAD src0_sel:WORD_1 src1_sel:DWORD
	v_and_b32_sdwa v20, v14, v152 dst_sel:DWORD dst_unused:UNUSED_PAD src0_sel:WORD_1 src1_sel:DWORD
	v_add3_u32 v57, v15, v19, s20
	v_add3_u32 v58, v14, v20, s20
	v_and_b32_e32 v15, 0xffff0000, v57
	v_and_b32_e32 v14, 0xffff0000, v58
	v_pk_mul_f32 v[14:15], v[14:15], v[14:15]
	v_xor_b32_e32 v2, 0x80000000, v2
	v_add_f32_e32 v14, v14, v18
	v_add_f32_e32 v18, v15, v14
	v_and_b32_e32 v15, 0xffff0000, v21
	v_lshlrev_b32_e32 v14, 16, v21
	v_pk_mul_f32 v[14:15], v[14:15], s[12:13] op_sel_hi:[1,0]
	v_perm_b32 v36, v36, v41, s24
	v_and_b32_sdwa v19, v15, v152 dst_sel:DWORD dst_unused:UNUSED_PAD src0_sel:WORD_1 src1_sel:DWORD
	v_and_b32_sdwa v20, v14, v152 dst_sel:DWORD dst_unused:UNUSED_PAD src0_sel:WORD_1 src1_sel:DWORD
	v_add3_u32 v59, v15, v19, s20
	v_add3_u32 v60, v14, v20, s20
	v_and_b32_e32 v15, 0xffff0000, v59
	v_and_b32_e32 v14, 0xffff0000, v60
	v_pk_mul_f32 v[14:15], v[14:15], v[14:15]
	v_add_u32_e32 v19, 1, v17
	v_add_f32_e32 v14, v14, v18
	v_add_f32_e32 v14, v15, v14
	ds_bpermute_b32 v15, v156, v14
	v_cndmask_b32_e64 v18, v17, v22, s[0:1]
	v_fma_f32 v17, -v19, v17, v16
	v_cmp_lt_f32_e64 s[0:1], 0, v17
	v_perm_b32 v35, v39, v40, s24
	s_waitcnt lgkmcnt(0)
	v_add_f32_e32 v14, v14, v15
	ds_bpermute_b32 v15, v155, v14
	v_cndmask_b32_e64 v17, v18, v19, s[0:1]
	v_mul_f32_e32 v18, 0x37800000, v17
	v_cndmask_b32_e32 v17, v17, v18, vcc
	v_cmp_class_f32_e64 s[0:1], v16, v151
	s_waitcnt lgkmcnt(0)
	v_add_f32_e32 v14, v14, v15
	v_mul_f32_e32 v6, v6, v14
	v_mul_f32_e32 v14, 0x4f800000, v6
	v_cmp_gt_f32_e32 vcc, s21, v6
	v_perm_b32 v34, v38, v9, s24
	v_perm_b32 v41, v59, v60, s24
	v_cndmask_b32_e32 v18, v6, v14, vcc
	v_sqrt_f32_e32 v19, v18
	v_cndmask_b32_e64 v6, v17, v16, s[0:1]
	v_xor_b32_e32 v6, 0x80000000, v6
	s_waitcnt vmcnt(0)
	v_and_b32_e32 v15, 0xffff0000, v10
	v_lshlrev_b32_e32 v14, 16, v10
	v_pk_mul_f32 v[14:15], v[14:15], s[12:13] op_sel_hi:[1,0]
	v_add_u32_e32 v16, -1, v19
	v_and_b32_sdwa v20, v14, v152 dst_sel:DWORD dst_unused:UNUSED_PAD src0_sel:WORD_1 src1_sel:DWORD
	v_and_b32_sdwa v10, v15, v152 dst_sel:DWORD dst_unused:UNUSED_PAD src0_sel:WORD_1 src1_sel:DWORD
	v_add3_u32 v62, v14, v20, s20
	v_add3_u32 v61, v15, v10, s20
	v_and_b32_e32 v10, 0xffff0000, v62
	v_mul_f32_e32 v20, v10, v10
	v_and_b32_e32 v10, 0xffff0000, v61
	v_and_b32_e32 v15, 0xffff0000, v11
	v_lshlrev_b32_e32 v14, 16, v11
	v_fmac_f32_e32 v20, v10, v10
	v_pk_mul_f32 v[10:11], v[14:15], s[12:13] op_sel_hi:[1,0]
	v_fma_f32 v17, -v16, v19, v18
	v_and_b32_sdwa v14, v11, v152 dst_sel:DWORD dst_unused:UNUSED_PAD src0_sel:WORD_1 src1_sel:DWORD
	v_and_b32_sdwa v15, v10, v152 dst_sel:DWORD dst_unused:UNUSED_PAD src0_sel:WORD_1 src1_sel:DWORD
	v_add3_u32 v63, v11, v14, s20
	v_add3_u32 v64, v10, v15, s20
	v_and_b32_e32 v11, 0xffff0000, v63
	v_and_b32_e32 v10, 0xffff0000, v64
	v_pk_mul_f32 v[10:11], v[10:11], v[10:11]
	v_cmp_ge_f32_e64 s[0:1], 0, v17
	v_add_f32_e32 v10, v10, v20
	v_add_f32_e32 v14, v11, v10
	v_and_b32_e32 v11, 0xffff0000, v12
	v_lshlrev_b32_e32 v10, 16, v12
	v_pk_mul_f32 v[10:11], v[10:11], s[12:13] op_sel_hi:[1,0]
	v_perm_b32 v40, v57, v58, s24
	v_and_b32_sdwa v12, v11, v152 dst_sel:DWORD dst_unused:UNUSED_PAD src0_sel:WORD_1 src1_sel:DWORD
	v_and_b32_sdwa v15, v10, v152 dst_sel:DWORD dst_unused:UNUSED_PAD src0_sel:WORD_1 src1_sel:DWORD
	v_add3_u32 v65, v11, v12, s20
	v_add3_u32 v66, v10, v15, s20
	v_and_b32_e32 v11, 0xffff0000, v65
	v_and_b32_e32 v10, 0xffff0000, v66
	v_pk_mul_f32 v[10:11], v[10:11], v[10:11]
	v_perm_b32 v39, v55, v56, s24
	v_add_f32_e32 v10, v10, v14
	v_add_f32_e32 v12, v11, v10
	v_and_b32_e32 v11, 0xffff0000, v13
	v_lshlrev_b32_e32 v10, 16, v13
	v_pk_mul_f32 v[10:11], v[10:11], s[12:13] op_sel_hi:[1,0]
	v_perm_b32 v38, v51, v54, s24
	v_and_b32_sdwa v13, v11, v152 dst_sel:DWORD dst_unused:UNUSED_PAD src0_sel:WORD_1 src1_sel:DWORD
	v_and_b32_sdwa v14, v10, v152 dst_sel:DWORD dst_unused:UNUSED_PAD src0_sel:WORD_1 src1_sel:DWORD
	v_add3_u32 v67, v11, v13, s20
	v_add3_u32 v68, v10, v14, s20
	v_and_b32_e32 v11, 0xffff0000, v67
	v_and_b32_e32 v10, 0xffff0000, v68
	v_pk_mul_f32 v[10:11], v[10:11], v[10:11]
	v_add_u32_e32 v13, 1, v19
	v_add_f32_e32 v10, v10, v12
	v_add_f32_e32 v10, v11, v10
	ds_bpermute_b32 v11, v156, v10
	v_fma_f32 v14, -v13, v19, v18
	v_cndmask_b32_e64 v12, v19, v16, s[0:1]
	v_cmp_lt_f32_e64 s[0:1], 0, v14
	v_mov_b32_e32 v9, v6
	s_waitcnt lgkmcnt(0)
	v_add_f32_e32 v10, v10, v11
	ds_bpermute_b32 v11, v155, v10
	v_cndmask_b32_e64 v12, v12, v13, s[0:1]
	v_mul_f32_e32 v13, 0x37800000, v12
	v_cndmask_b32_e32 v12, v12, v13, vcc
	v_cmp_class_f32_e64 s[0:1], v18, v151
	s_waitcnt lgkmcnt(0)
	v_add_f32_e32 v10, v10, v11
	v_mul_f32_e32 v7, v7, v10
	v_mul_f32_e32 v10, 0x4f800000, v7
	v_cmp_gt_f32_e32 vcc, s21, v7
	v_perm_b32 v45, v45, v49, s24
	v_perm_b32 v44, v44, v48, s24
	v_cndmask_b32_e32 v7, v7, v10, vcc
	v_sqrt_f32_e32 v11, v7
	v_cndmask_b32_e64 v10, v12, v18, s[0:1]
	v_xor_b32_e32 v10, 0x80000000, v10
	v_perm_b32 v43, v43, v47, s24
	v_add_u32_e32 v12, -1, v11
	v_fma_f32 v13, -v12, v11, v7
	v_cmp_ge_f32_e64 s[0:1], 0, v13
	v_add_u32_e32 v13, 1, v11
	v_perm_b32 v42, v42, v46, s24
	v_cndmask_b32_e64 v12, v11, v12, s[0:1]
	v_fma_f32 v11, -v13, v11, v7
	v_cmp_lt_f32_e64 s[0:1], 0, v11
	v_perm_b32 v49, v67, v68, s24
	v_perm_b32 v48, v65, v66, s24
	v_cndmask_b32_e64 v11, v12, v13, s[0:1]
	v_mul_f32_e32 v12, 0x37800000, v11
	v_cndmask_b32_e32 v11, v11, v12, vcc
	v_cmp_class_f32_e32 vcc, v7, v151
	s_add_u32 s0, s3, s35
	s_addc_u32 s1, s13, s34
	v_cndmask_b32_e32 v7, v11, v7, vcc
	s_and_b32 s36, s30, 0xffffff00
	v_xor_b32_e32 v14, 0x80000000, v7
	v_add_u32_e32 v7, s36, v159
	v_add_u32_e32 v11, 0x8000, v7
	v_mad_i64_i32 v[12:13], s[34:35], v11, s19, v[4:5]
	v_lshlrev_b32_e32 v11, 3, v50
	v_add_u32_e32 v7, 0x8040, v7
	v_and_b32_e32 v11, 56, v11
	v_mov_b64_e32 v[16:17], s[0:1]
	v_mad_i64_i32 v[4:5], s[0:1], v7, s19, v[4:5]
	v_lshl_add_u64 v[12:13], v[12:13], 0, s[10:11]
	v_lshlrev_b32_e32 v142, 1, v11
	v_lshl_add_u64 v[4:5], v[4:5], 0, s[10:11]
	v_lshl_add_u64 v[12:13], v[12:13], 0, v[142:143]
	v_mad_i64_i32 v[16:17], s[0:1], v159, s22, v[16:17]
	v_lshl_add_u64 v[4:5], v[4:5], 0, v[142:143]
	v_lshl_add_u64 v[16:17], v[16:17], 0, v[142:143]
	global_load_dwordx4 v[18:21], v[12:13], off offset:3648
	global_load_dwordx4 v[22:25], v[16:17], off
	global_load_dwordx4 v[26:29], v[4:5], off offset:3648
	global_load_dwordx4 v[30:33], v[16:17], off offset:128
	v_mad_i64_i32 v[52:53], s[34:35], v159, s22, 0
	v_lshrrev_b32_e32 v4, 1, v159
	s_add_i32 s34, s36, 0x8080
	s_add_i32 s35, s36, 0x80c0
	v_xor_b32_e32 v4, v4, v50
	s_add_u32 s0, s60, s10
	v_lshlrev_b32_e32 v4, 3, v4
	s_addc_u32 s1, s61, 0
	v_and_b32_e32 v70, 56, v4
	v_bfe_u32 v4, v50, 1, 3
	v_lshl_add_u64 v[144:145], s[0:1], 0, v[142:143]
	v_mad_i64_i32 v[52:53], s[0:1], s2, v153, v[52:53]
	v_and_b32_e32 v50, 7, v50
	v_xor_b32_e32 v5, v8, v4
	v_bitop3_b32 v3, v8, v4, 4 bitop3:0x36
	v_lshl_or_b32 v52, v50, 4, v52
	v_lshlrev_b32_e32 v161, 3, v5
	v_lshlrev_b32_e32 v162, 3, v3
	v_mov_b32_e32 v3, v2
	v_mov_b32_e32 v4, v2
	v_mov_b32_e32 v5, v2
	v_mov_b32_e32 v11, v10
	v_mov_b32_e32 v12, v10
	v_mov_b32_e32 v13, v10
	v_mov_b32_e32 v7, v6
	v_mov_b32_e32 v8, v6
	v_mov_b32_e32 v15, v14
	v_mov_b32_e32 v16, v14
	v_mov_b32_e32 v17, v14
	v_perm_b32 v47, v63, v64, s24
	v_perm_b32 v46, v61, v62, s24
	v_lshl_add_u64 v[146:147], s[8:9], 0, v[52:53]
	v_lshlrev_b32_e32 v143, 1, v69
	v_lshlrev_b32_e32 v163, 1, v70
	s_mov_b32 s10, 0
	s_mov_b32 s36, 0
	v_mov_b32_e32 v66, 0
	v_mov_b32_e32 v67, v135
	v_mov_b32_e32 v68, v135
	v_mov_b32_e32 v69, v135
	v_mov_b32_e32 v50, 0
	v_mov_b32_e32 v51, v135
	v_mov_b32_e32 v52, v135
	v_mov_b32_e32 v53, v135
	v_mov_b32_e32 v54, 0
	v_mov_b32_e32 v55, v135
	v_mov_b32_e32 v56, v135
	v_mov_b32_e32 v57, v135
	v_mov_b32_e32 v58, 0
	v_mov_b32_e32 v59, v135
	v_mov_b32_e32 v60, v135
	v_mov_b32_e32 v61, v135
	v_mov_b32_e32 v62, 0
	v_mov_b32_e32 v63, v135
	v_mov_b32_e32 v64, v135
	v_mov_b32_e32 v65, v135
	v_mov_b32_e32 v70, 0
	v_mov_b32_e32 v123, v135
	v_mov_b32_e32 v124, v135
	v_mov_b32_e32 v125, v135
	v_mov_b32_e32 v82, 0
	v_mov_b32_e32 v83, v135
	v_mov_b32_e32 v84, v135
	v_mov_b32_e32 v85, v135
	v_mov_b32_e32 v86, 0
	v_mov_b32_e32 v87, v135
	v_mov_b32_e32 v88, v135
	v_mov_b32_e32 v89, v135
	v_mov_b32_e32 v114, 0
	v_mov_b32_e32 v115, v135
	v_mov_b32_e32 v116, v135
	v_mov_b32_e32 v117, v135
	v_mov_b32_e32 v126, 0
	v_mov_b32_e32 v127, v135
	v_mov_b32_e32 v128, v135
	v_mov_b32_e32 v129, v135
	v_lshlrev_b32_e32 v246, 1, v160
	v_lshl_add_u32 v247, v162, 1, v246
	v_lshl_add_u32 v246, v161, 1, v246
	v_lshl_add_u32 v248, v158, 1, v165
	v_add_u32_e32 v244, v143, v163
	v_add_u32_e32 v245, v164, v142
	v_mov_b64_e32 v[240:241], s[4:5]
	v_mov_b64_e32 v[242:243], s[6:7]
	v_readfirstlane_b32 s98, v1
	s_cmpk_lt_u32 s98, 0x100
	s_cbranch_scc1 .Lnoprio_2159
	s_setprio 1
.Lnoprio_2159:
	s_movk_i32 s99, 0x4800
	v_lshlrev_b32_e32 v134, 1, v158
	s_barrier
	s_branch .LBB0_2160

.LBB0_2162:
	s_setprio 0
	v_cmp_gt_u32_e32 vcc, 32, v157
	v_mov_b32_e32 v2, 0
	v_mov_b32_e32 v3, 0
	s_and_saveexec_b64 s[0:1], vcc
	s_cbranch_execz .LBB0_2157
	v_readlane_b32 s36, v239, 1
	v_lshlrev_b32_e32 v5, 2, v157
	v_readlane_b32 s38, v239, 3
	v_readlane_b32 s39, v239, 4
	v_readlane_b32 s40, v239, 5
	v_readlane_b32 s41, v239, 6
	v_readlane_b32 s42, v239, 7
	v_readlane_b32 s43, v239, 8
	v_readlane_b32 s44, v239, 9
	v_readlane_b32 s45, v239, 10
	global_load_dword v2, v5, s[38:39] offset:128
	global_load_dword v4, v5, s[40:41] offset:128
	s_nop 0
	global_load_dword v3, v5, s[42:43] offset:128
	s_nop 0
	global_load_dword v5, v5, s[44:45] offset:128
	v_readlane_b32 s37, v239, 2
	v_readlane_b32 s46, v239, 11
	v_readlane_b32 s47, v239, 12
	v_readlane_b32 s48, v239, 13
	v_readlane_b32 s49, v239, 14
	v_readlane_b32 s50, v239, 15
	v_readlane_b32 s51, v239, 16
	s_waitcnt vmcnt(0)
	v_pk_mul_f32 v[2:3], v[2:3], v[4:5]
	s_branch .LBB0_2157
